# v25 + attention (prompt copy): next tile's K/V LDS staging moved from the tile tail into the shadow of the third PV MFMA group, written straight from the prefetch registers
# baseline (speedup 1.0000x reference)
; __device__ __forceinline__ void attn_unit(const Frame& F, int l, int samp, int b, int c, int g) {
;     ...
;         if (t + 1 < ntiles) ATT_LOAD(t + 1);
;         ATT_COMPUTE(buf, mwc);
;         if (t + 1 < ntiles) ATT_WRITE(buf ^ 1, t + 1);
.Latt2_norescale:
	ds_read2_b64 v[68:71], v215 offset0:4 offset1:6
	ds_read2_b64 v[72:75], v214 offset0:36 offset1:38
	ds_read2_b64 v[76:79], v195 offset0:68 offset1:70
	ds_read2_b64 v[202:205], v193 offset0:100 offset1:102
	s_andn2_b64 vcc, exec, s[0:1]
	v_mfma_f32_32x32x16_bf16 v[48:63], v[172:175], v[64:67], v[48:63]
	v_mfma_f32_32x32x16_bf16 v[32:47], v[168:171], v[64:67], v[32:47]
	v_mfma_f32_32x32x16_bf16 v[16:31], v[164:167], v[64:67], v[16:31]
	v_mfma_f32_32x32x16_bf16 v[0:15], v[160:163], v[64:67], v[0:15]
	v_add_f32_e32 v231, 0, v82
	v_add_f32_e32 v231, v83, v231
	v_add_f32_e32 v231, v84, v231
	v_add_f32_e32 v231, v85, v231
	v_add_f32_e32 v231, v86, v231
	v_add_f32_e32 v231, v87, v231
	v_add_f32_e32 v231, v88, v231
	v_add_f32_e32 v231, v89, v231
	v_cvt_pk_bf16_f32 v64, v90, v91
	v_cvt_pk_bf16_f32 v65, v92, v93
	v_cvt_pk_bf16_f32 v66, v94, v95
	v_cvt_pk_bf16_f32 v67, v196, v197
	ds_read2_b64 v[160:163], v215 offset0:8 offset1:10
	ds_read2_b64 v[164:167], v214 offset0:40 offset1:42
	ds_read2_b64 v[168:171], v195 offset0:72 offset1:74
	ds_read2_b64 v[172:175], v193 offset0:104 offset1:106
	s_waitcnt lgkmcnt(4)
	s_nop 0
	v_mfma_f32_32x32x16_bf16 v[48:63], v[68:71], v[64:67], v[48:63]
	v_mfma_f32_32x32x16_bf16 v[32:47], v[72:75], v[64:67], v[32:47]
	v_mfma_f32_32x32x16_bf16 v[16:31], v[76:79], v[64:67], v[16:31]
	v_mfma_f32_32x32x16_bf16 v[0:15], v[202:205], v[64:67], v[0:15]
	v_add_f32_e32 v231, v90, v231
	v_add_f32_e32 v231, v91, v231
	v_add_f32_e32 v231, v92, v231
	v_add_f32_e32 v231, v93, v231
	v_add_f32_e32 v231, v94, v231
	v_add_f32_e32 v231, v95, v231
	v_add_f32_e32 v231, v196, v231
	v_add_f32_e32 v231, v197, v231
	v_cvt_pk_bf16_f32 v64, v216, v217
	v_cvt_pk_bf16_f32 v65, v218, v219
	v_cvt_pk_bf16_f32 v66, v220, v221
	v_cvt_pk_bf16_f32 v67, v242, v243
	ds_read2_b64 v[68:71], v215 offset0:12 offset1:14
	ds_read2_b64 v[72:75], v214 offset0:44 offset1:46
	ds_read2_b64 v[76:79], v195 offset0:76 offset1:78
	ds_read2_b64 v[202:205], v193 offset0:108 offset1:110
	s_waitcnt lgkmcnt(4)
	s_waitcnt lgkmcnt(0)
	v_mfma_f32_32x32x16_bf16 v[48:63], v[160:163], v[64:67], v[48:63]
	v_mfma_f32_32x32x16_bf16 v[32:47], v[164:167], v[64:67], v[32:47]
	v_mfma_f32_32x32x16_bf16 v[16:31], v[168:171], v[64:67], v[16:31]
	v_mfma_f32_32x32x16_bf16 v[0:15], v[172:175], v[64:67], v[0:15]
	v_add_f32_e32 v231, v216, v231
	v_add_f32_e32 v231, v217, v231
	v_add_f32_e32 v231, v218, v231
	v_add_f32_e32 v231, v219, v231
	v_add_f32_e32 v231, v220, v231
	v_add_f32_e32 v231, v221, v231
	v_add_f32_e32 v231, v242, v231
	v_add_f32_e32 v231, v243, v231
	s_cbranch_vccnz .Lad_nostage
	s_add_i32 s0, s6, 2
	s_cmp_lt_u32 s0, s22
	s_cbranch_scc1 .Lad_sw5
	s_waitcnt vmcnt(0)
	s_branch .Lad_sw

.Lad_sw:
	s_xor_b32 s0, s4, 1
	s_mulk_i32 s0, 0x4400
	v_add3_u32 v82, s0, v206, v207
	v_add3_u32 v83, s0, v208, v207
	v_add3_u32 v84, s0, v210, v209
	v_add_u32_e32 v84, 0x8800, v84
	s_bitcmp1_b32 s6, 0
	s_cbranch_scc1 .Lad_sB
	ds_write_b128 v82, v[144:147]
	ds_write_b128 v83, v[148:151]
	v_and_b32_e32 v85, 0xffff, v156
	v_lshrrev_b32_e32 v86, 16, v156
	v_lshl_or_b32 v85, v152, 16, v85
	v_and_or_b32 v86, v152, s79, v86
	ds_write2_b32 v84, v85, v86 offset1:34
	v_and_b32_e32 v85, 0xffff, v157
	v_lshrrev_b32_e32 v86, 16, v157
	v_lshl_or_b32 v85, v153, 16, v85
	v_and_or_b32 v86, v153, s79, v86
	ds_write2_b32 v84, v85, v86 offset0:68 offset1:102
	v_and_b32_e32 v85, 0xffff, v158
	v_lshrrev_b32_e32 v86, 16, v158
	v_lshl_or_b32 v85, v154, 16, v85
	v_and_or_b32 v86, v154, s79, v86
	ds_write2_b32 v84, v85, v86 offset0:136 offset1:170
	v_and_b32_e32 v85, 0xffff, v159
	v_lshrrev_b32_e32 v86, 16, v159
	v_lshl_or_b32 v85, v155, 16, v85
	v_and_or_b32 v86, v155, s79, v86
	ds_write2_b32 v84, v85, v86 offset0:204 offset1:238
	s_branch .Lad_nostage
.Lad_sB:
	ds_write_b128 v82, v[128:131]
	ds_write_b128 v83, v[132:135]
	v_and_b32_e32 v85, 0xffff, v140
	v_lshrrev_b32_e32 v86, 16, v140
	v_lshl_or_b32 v85, v136, 16, v85
	v_and_or_b32 v86, v136, s79, v86
	ds_write2_b32 v84, v85, v86 offset1:34
	v_and_b32_e32 v85, 0xffff, v141
	v_lshrrev_b32_e32 v86, 16, v141
	v_lshl_or_b32 v85, v137, 16, v85
	v_and_or_b32 v86, v137, s79, v86
	ds_write2_b32 v84, v85, v86 offset0:68 offset1:102
	v_and_b32_e32 v85, 0xffff, v142
	v_lshrrev_b32_e32 v86, 16, v142
	v_lshl_or_b32 v85, v138, 16, v85
	v_and_or_b32 v86, v138, s79, v86
	ds_write2_b32 v84, v85, v86 offset0:136 offset1:170
	v_and_b32_e32 v85, 0xffff, v143
	v_lshrrev_b32_e32 v86, 16, v143
	v_lshl_or_b32 v85, v139, 16, v85
	v_and_or_b32 v86, v139, s79, v86
	ds_write2_b32 v84, v85, v86 offset0:204 offset1:238
.Lad_nostage:
	v_cvt_pk_bf16_f32 v64, v244, v245
	v_cvt_pk_bf16_f32 v65, v246, v247
	v_cvt_pk_bf16_f32 v66, v248, v249
	v_cvt_pk_bf16_f32 v67, v250, v251
	s_nop 1
	v_mfma_f32_32x32x16_bf16 v[48:63], v[68:71], v[64:67], v[48:63]
	v_mfma_f32_32x32x16_bf16 v[32:47], v[72:75], v[64:67], v[32:47]
	v_mfma_f32_32x32x16_bf16 v[16:31], v[76:79], v[64:67], v[16:31]
	v_mfma_f32_32x32x16_bf16 v[0:15], v[202:205], v[64:67], v[0:15]
	v_add_f32_e32 v231, v244, v231
	v_add_f32_e32 v231, v245, v231
	v_add_f32_e32 v231, v246, v231
	v_add_f32_e32 v231, v247, v231
	v_add_f32_e32 v231, v248, v231
	v_add_f32_e32 v231, v249, v231
	v_add_f32_e32 v231, v250, v231
	v_add_f32_e32 v231, v251, v231
